# differential-attention epilogue: gate and sub-norm weight loads prefetched in batches (no per-row round trips)
# speedup vs baseline: 1.0054x; 1.0049x over previous
; DI float bflo(unsigned u) { return __uint_as_float(u << 16); }
; DI float bfhi(unsigned u) { return __uint_as_float(u & 0xffff0000u); }
; DI float shx(float v, int m, int lane) { return __int_as_float(__builtin_amdgcn_ds_bpermute((lane ^ m) << 2, __float_as_int(v))); }
; __global__ void __launch_bounds__(512) mega(Params P) {
;     ...
;                     if (map == 0) {
;                         const float* lv = P.diff_lambda + l * 256;
;                         const float d01 = wave_sum(lv[l2] * lv[64 + l2], l2), d23 = wave_sum(lv[128 + l2] * lv[192 + l2], l2);
;                         const float lambda_init = 0.8f - 0.6f * expf(-0.3f * (float)l);
;                         const float lam = expf(d01) - expf(d23) + lambda_init;
;                         float ss = 0.f;
; #pragma unroll
;                         for (int d0 = 0; d0 < 4; ++d0)
; #pragma unroll
;                             for (int r = 0; r < 16; ++r) { const float v = o[d0][r] * linv - lam * xch[(d0 * 16 + r) * 256 + wid * 64 + l2]; o[d0][r] = v; ss += v * v; }
;                         ss += shx(ss, 32, l2);
;                         const float rn = rsqrtf(ss * (1.0f / 128.0f) + EPS) * (1.0f - lambda_init);
;                         const int token = q02 + (l2 & 31); const float* sw = P.diff_subnorm + l * 128;
; #pragma unroll
;                         for (int d0 = 0; d0 < 4; ++d0) {
; #pragma unroll
;                             for (int g = 0; g < 4; ++g) {
;                                 const int dv = 32 * d0 + 8 * g + 4 * hi2, col = 1536 + h2 * 128 + dv;
;                                 const u32x2 gv = *(const u32x2*)(proj + (size_t)token * LDP + C_SILU + col);
;                                 const f32x4 w = *(const f32x4*)(sw + dv);
;                                 u32x2 ov;
;                                 ov.x = cvt_pk(o[d0][4 * g + 0] * rn * w.x * bflo(gv.x), o[d0][4 * g + 1] * rn * w.y * bfhi(gv.x));
;                                 ov.y = cvt_pk(o[d0][4 * g + 2] * rn * w.z * bflo(gv.y), o[d0][4 * g + 3] * rn * w.w * bfhi(gv.y));
;                                 *(u32x2*)(Yb + (size_t)token * DM + col) = ov;
.LBB0_482:
	s_andn2_b64 vcc, exec, s[34:35]
	s_waitcnt lgkmcnt(0)
	s_barrier
	s_cbranch_vccnz .LBB0_450
	v_ashrrev_i32_e32 v81, 31, v80
	v_lshl_add_u64 v[82:83], v[80:81], 2, s[8:9]
	global_load_dword v85, v[82:83], off
	global_load_dword v88, v[82:83], off offset:256
	global_load_dword v89, v[82:83], off offset:512
	global_load_dword v90, v[82:83], off offset:768
	v_lshlrev_b32_e32 v81, 2, v80
	s_lshl_b32 s29, s48, 7
	v_xor_b32_e32 v86, 4, v81
	s_lshl_b32 s36, s48, 1
	s_and_b32 s29, s29, 0x1f80
	v_ashrrev_i32_e32 v84, 3, v80
	s_and_b32 s48, s36, 0xffffff80
	v_and_or_b32 v80, v80, 31, s29
	v_mov_b64_e32 v[82:83], s[30:31]
	v_and_b32_e32 v84, -4, v84
	s_add_i32 s50, s48, 0x600
	v_or_b32_e32 v136, s14, v80
	v_add_u32_e32 v80, s50, v84
	v_mad_u64_u32 v[82:83], s[52:53], v136, s68, v[82:83]
	v_xor_b32_e32 v94, 8, v81
	v_xor_b32_e32 v95, 16, v81
	v_xor_b32_e32 v96, 32, v81
	v_xor_b32_e32 v97, 64, v81
	v_xor_b32_e32 v93, 0x80, v81
	v_add_u32_e32 v134, s86, v81
	v_ashrrev_i32_e32 v81, 31, v80
	ds_read2st64_b32 v[106:107], v134 offset1:4
	ds_read2st64_b32 v[112:113], v134 offset0:8 offset1:12
	ds_read2st64_b32 v[132:133], v134 offset0:16 offset1:20
	ds_read2st64_b32 v[114:115], v134 offset0:24 offset1:28
	ds_read2st64_b32 v[122:123], v134 offset0:32 offset1:36
	ds_read2st64_b32 v[108:109], v134 offset0:40 offset1:44
	ds_read2st64_b32 v[174:175], v134 offset0:48 offset1:52
	ds_read2st64_b32 v[176:177], v134 offset0:56 offset1:60
	ds_read2st64_b32 v[166:167], v134 offset0:64 offset1:68
	ds_read2st64_b32 v[168:169], v134 offset0:72 offset1:76
	ds_read2st64_b32 v[158:159], v134 offset0:80 offset1:84
	ds_read2st64_b32 v[160:161], v134 offset0:88 offset1:92
	ds_read2st64_b32 v[150:151], v134 offset0:96 offset1:100
	ds_read2st64_b32 v[152:153], v134 offset0:104 offset1:108
	ds_read2st64_b32 v[144:145], v134 offset0:112 offset1:116
	ds_read2st64_b32 v[146:147], v134 offset0:120 offset1:124
	ds_read2st64_b32 v[140:141], v134 offset0:128 offset1:132
	ds_read2st64_b32 v[142:143], v134 offset0:136 offset1:140
	ds_read2st64_b32 v[120:121], v134 offset0:144 offset1:148
	ds_read2st64_b32 v[126:127], v134 offset0:152 offset1:156
	s_mov_b32 s29, 0x3fb8aa3b
	v_mov_b32_e32 v91, v129
	s_ashr_i32 s49, s48, 31
	s_waitcnt vmcnt(2)
	v_mul_f32_e32 v87, v85, v88
	ds_bpermute_b32 v99, v86, v87
	s_waitcnt vmcnt(0)
	v_mul_f32_e32 v98, v89, v90
	ds_bpermute_b32 v98, v86, v98
	v_lshl_add_u64 v[86:87], v[82:83], 0, s[88:89]
	v_lshl_add_u64 v[80:81], v[80:81], 1, v[86:87]
	s_waitcnt lgkmcnt(1)
	v_fmac_f32_e32 v99, v85, v88
	global_load_dwordx2 v[118:119], v[80:81], off
	global_load_dwordx2 v[222:223], v[80:81], off offset:16
	global_load_dwordx2 v[224:225], v[80:81], off offset:32
	global_load_dwordx2 v[226:227], v[80:81], off offset:48
	global_load_dwordx2 v[228:229], v[80:81], off offset:64
	global_load_dwordx2 v[230:231], v[80:81], off offset:80
	global_load_dwordx2 v[232:233], v[80:81], off offset:96
	global_load_dwordx2 v[234:235], v[80:81], off offset:112
	global_load_dwordx2 v[236:237], v[80:81], off offset:128
	global_load_dwordx2 v[238:239], v[80:81], off offset:144
	global_load_dwordx2 v[240:241], v[80:81], off offset:160
	global_load_dwordx2 v[242:243], v[80:81], off offset:176
	global_load_dwordx2 v[244:245], v[80:81], off offset:192
	global_load_dwordx2 v[246:247], v[80:81], off offset:208
	global_load_dwordx2 v[248:249], v[80:81], off offset:224
	global_load_dwordx2 v[250:251], v[80:81], off offset:240
	s_waitcnt lgkmcnt(0)
	v_fmac_f32_e32 v98, v89, v90
	ds_bpermute_b32 v80, v94, v99
	ds_bpermute_b32 v81, v94, v98
	v_lshlrev_b32_e32 v90, 12, v136
	ds_read2st64_b32 v[130:131], v134 offset0:160 offset1:164
	ds_read2st64_b32 v[138:139], v134 offset0:168 offset1:172
	ds_read2st64_b32 v[110:111], v134 offset0:176 offset1:180
	ds_read2st64_b32 v[124:125], v134 offset0:184 offset1:188
	ds_read2st64_b32 v[102:103], v134 offset0:192 offset1:196
	ds_read2st64_b32 v[104:105], v134 offset0:200 offset1:204
	s_waitcnt lgkmcnt(7)
	v_add_f32_e32 v80, v99, v80
	s_waitcnt lgkmcnt(6)
	v_add_f32_e32 v81, v98, v81
	ds_bpermute_b32 v82, v95, v80
	ds_bpermute_b32 v83, v95, v81
	ds_read2st64_b32 v[98:99], v134 offset0:208 offset1:212
	ds_read2st64_b32 v[100:101], v134 offset0:216 offset1:220
	ds_read2st64_b32 v[94:95], v134 offset0:224 offset1:228
	v_ashrrev_i32_e32 v85, 31, v84
	v_lshl_add_u64 v[88:89], v[84:85], 2, s[16:17]
	s_waitcnt lgkmcnt(4)
	v_add_f32_e32 v80, v80, v82
	s_waitcnt lgkmcnt(3)
	v_add_f32_e32 v81, v81, v83
	ds_bpermute_b32 v82, v96, v80
	ds_bpermute_b32 v83, v96, v81
	v_lshl_add_u64 v[90:91], s[10:11], 0, v[90:91]
	s_waitcnt lgkmcnt(1)
	v_add_f32_e32 v80, v80, v82
	s_waitcnt lgkmcnt(0)
	v_add_f32_e32 v81, v81, v83
	ds_bpermute_b32 v82, v97, v80
	ds_bpermute_b32 v83, v97, v81
	ds_read2st64_b32 v[96:97], v134 offset0:232 offset1:236
	ds_read2st64_b32 v[116:117], v134 offset0:240 offset1:244
	ds_read2st64_b32 v[134:135], v134 offset0:248 offset1:252
	s_waitcnt lgkmcnt(4)
	v_add_f32_e32 v80, v80, v82
	s_waitcnt lgkmcnt(3)
	v_add_f32_e32 v81, v81, v83
	ds_bpermute_b32 v82, v93, v80
	ds_bpermute_b32 v83, v93, v81
	s_waitcnt lgkmcnt(1)
	v_add_f32_e32 v136, v80, v82
	s_waitcnt lgkmcnt(0)
; DI float shx(float v, int m, int lane) { return __int_as_float(__builtin_amdgcn_ds_bpermute((lane ^ m) << 2, __float_as_int(v))); }
; __global__ void __launch_bounds__(512) mega(Params P) {
;     ...
;                         const float* lv = P.diff_lambda + l * 256;
;                         const float d01 = wave_sum(lv[l2] * lv[64 + l2], l2), d23 = wave_sum(lv[128 + l2] * lv[192 + l2], l2);
;                         const float lambda_init = 0.8f - 0.6f * expf(-0.3f * (float)l);
;                         const float lam = expf(d01) - expf(d23) + lambda_init;
;                         float ss = 0.f;
; #pragma unroll
;                         for (int d0 = 0; d0 < 4; ++d0)
; #pragma unroll
;                             for (int r = 0; r < 16; ++r) { const float v = o[d0][r] * linv - lam * xch[(d0 * 16 + r) * 256 + wid * 64 + l2]; o[d0][r] = v; ss += v * v; }
;                         ss += shx(ss, 32, l2);
;                         const float rn = rsqrtf(ss * (1.0f / 128.0f) + EPS) * (1.0f - lambda_init);
	v_add_f32_e32 v137, v81, v83
	v_mul_f32_e32 v80, 0x3fb8aa3b, v136
	v_mul_f32_e32 v81, 0x3fb8aa3b, v137
	v_fma_f32 v82, v136, s29, -v80
	v_rndne_f32_e32 v83, v80
	v_fma_f32 v148, v137, s29, -v81
	v_rndne_f32_e32 v149, v81
	v_fmac_f32_e32 v82, 0x32a5705f, v136
	v_sub_f32_e32 v80, v80, v83
	v_fmac_f32_e32 v148, 0x32a5705f, v137
	v_sub_f32_e32 v81, v81, v149
	v_add_f32_e32 v80, v80, v82
	v_cvt_i32_f32_e32 v154, v83
	v_add_f32_e32 v81, v81, v148
	v_exp_f32_e32 v148, v80
	v_cvt_i32_f32_e32 v149, v149
	v_exp_f32_e32 v155, v81
	s_mov_b32 s29, 0xc2ce8ed0
	v_ldexp_f32 v148, v148, v154
	v_cmp_ngt_f32_e32 vcc, s29, v136
	v_ldexp_f32 v149, v155, v149
	v_mov_b32_e32 v154, 0x7f800000
	v_cndmask_b32_e32 v148, 0, v148, vcc
	v_cmp_ngt_f32_e32 vcc, s29, v137
	s_mov_b32 s29, 0x42b17218
	global_load_dwordx4 v[80:83], v[88:89], off
	v_cndmask_b32_e32 v149, 0, v149, vcc
	v_cmp_nlt_f32_e32 vcc, s29, v136
	s_nop 1
	v_cndmask_b32_e32 v136, v154, v148, vcc
	v_cmp_nlt_f32_e32 vcc, s29, v137
	s_nop 1
	v_cndmask_b32_e32 v137, v154, v149, vcc
	v_sub_f32_e32 v136, v136, v137
	v_add_f32_e32 v148, v183, v136
	v_pk_mul_f32 v[112:113], v[148:149], v[112:113] op_sel_hi:[0,1]
	v_pk_mul_f32 v[136:137], v[148:149], v[106:107] op_sel_hi:[0,1]
	v_pk_fma_f32 v[106:107], v[92:93], v[66:67], v[112:113] op_sel_hi:[0,1,1] neg_lo:[0,0,1] neg_hi:[0,0,1]
	v_pk_fma_f32 v[112:113], v[92:93], v[64:65], v[136:137] op_sel_hi:[0,1,1] neg_lo:[0,0,1] neg_hi:[0,0,1]
	v_pk_mul_f32 v[64:65], v[148:149], v[114:115] op_sel_hi:[0,1]
	v_pk_fma_f32 v[114:115], v[92:93], v[70:71], v[64:65] op_sel_hi:[0,1,1] neg_lo:[0,0,1] neg_hi:[0,0,1]
	v_pk_mul_f32 v[64:65], v[148:149], v[132:133] op_sel_hi:[0,1]
	v_pk_fma_f32 v[132:133], v[92:93], v[68:69], v[64:65] op_sel_hi:[0,1,1] neg_lo:[0,0,1] neg_hi:[0,0,1]
	v_pk_mul_f32 v[64:65], v[148:149], v[108:109] op_sel_hi:[0,1]
	v_pk_fma_f32 v[108:109], v[92:93], v[74:75], v[64:65] op_sel_hi:[0,1,1] neg_lo:[0,0,1] neg_hi:[0,0,1]
	v_pk_mul_f32 v[64:65], v[148:149], v[122:123] op_sel_hi:[0,1]
	v_pk_fma_f32 v[122:123], v[92:93], v[72:73], v[64:65] op_sel_hi:[0,1,1] neg_lo:[0,0,1] neg_hi:[0,0,1]
	v_pk_mul_f32 v[64:65], v[148:149], v[176:177] op_sel_hi:[0,1]
	v_pk_fma_f32 v[72:73], v[92:93], v[78:79], v[64:65] op_sel_hi:[0,1,1] neg_lo:[0,0,1] neg_hi:[0,0,1]
	v_pk_mul_f32 v[64:65], v[148:149], v[174:175] op_sel_hi:[0,1]
	v_pk_fma_f32 v[76:77], v[92:93], v[76:77], v[64:65] op_sel_hi:[0,1,1] neg_lo:[0,0,1] neg_hi:[0,0,1]
	v_pk_mul_f32 v[64:65], v[148:149], v[168:169] op_sel_hi:[0,1]
	v_pk_fma_f32 v[68:69], v[92:93], v[50:51], v[64:65] op_sel_hi:[0,1,1] neg_lo:[0,0,1] neg_hi:[0,0,1]
	v_pk_mul_f32 v[50:51], v[148:149], v[166:167] op_sel_hi:[0,1]
	v_pk_fma_f32 v[74:75], v[92:93], v[48:49], v[50:51] op_sel_hi:[0,1,1] neg_lo:[0,0,1] neg_hi:[0,0,1]
	v_pk_mul_f32 v[48:49], v[148:149], v[160:161] op_sel_hi:[0,1]
	v_pk_fma_f32 v[64:65], v[92:93], v[54:55], v[48:49] op_sel_hi:[0,1,1] neg_lo:[0,0,1] neg_hi:[0,0,1]
	v_pk_mul_f32 v[48:49], v[148:149], v[158:159] op_sel_hi:[0,1]
	v_pk_fma_f32 v[70:71], v[92:93], v[52:53], v[48:49] op_sel_hi:[0,1,1] neg_lo:[0,0,1] neg_hi:[0,0,1]
	v_pk_mul_f32 v[48:49], v[148:149], v[152:153] op_sel_hi:[0,1]
	v_pk_fma_f32 v[58:59], v[92:93], v[58:59], v[48:49] op_sel_hi:[0,1,1] neg_lo:[0,0,1] neg_hi:[0,0,1]
	v_pk_mul_f32 v[48:49], v[148:149], v[150:151] op_sel_hi:[0,1]
	v_pk_fma_f32 v[66:67], v[92:93], v[56:57], v[48:49] op_sel_hi:[0,1,1] neg_lo:[0,0,1] neg_hi:[0,0,1]
	v_pk_mul_f32 v[48:49], v[148:149], v[146:147] op_sel_hi:[0,1]
	v_pk_fma_f32 v[54:55], v[92:93], v[62:63], v[48:49] op_sel_hi:[0,1,1] neg_lo:[0,0,1] neg_hi:[0,0,1]
	v_pk_mul_f32 v[48:49], v[148:149], v[144:145] op_sel_hi:[0,1]
	v_pk_fma_f32 v[60:61], v[92:93], v[60:61], v[48:49] op_sel_hi:[0,1,1] neg_lo:[0,0,1] neg_hi:[0,0,1]
	v_pk_mul_f32 v[48:49], v[148:149], v[142:143] op_sel_hi:[0,1]
	v_pk_fma_f32 v[50:51], v[92:93], v[34:35], v[48:49] op_sel_hi:[0,1,1] neg_lo:[0,0,1] neg_hi:[0,0,1]
	v_pk_mul_f32 v[34:35], v[148:149], v[140:141] op_sel_hi:[0,1]
	v_pk_fma_f32 v[56:57], v[92:93], v[32:33], v[34:35] op_sel_hi:[0,1,1] neg_lo:[0,0,1] neg_hi:[0,0,1]
	v_pk_mul_f32 v[32:33], v[148:149], v[126:127] op_sel_hi:[0,1]
	v_pk_fma_f32 v[48:49], v[92:93], v[38:39], v[32:33] op_sel_hi:[0,1,1] neg_lo:[0,0,1] neg_hi:[0,0,1]
	v_pk_mul_f32 v[32:33], v[148:149], v[120:121] op_sel_hi:[0,1]
	v_pk_fma_f32 v[52:53], v[92:93], v[36:37], v[32:33] op_sel_hi:[0,1,1] neg_lo:[0,0,1] neg_hi:[0,0,1]
	v_pk_mul_f32 v[32:33], v[148:149], v[138:139] op_sel_hi:[0,1]
	v_pk_fma_f32 v[38:39], v[92:93], v[42:43], v[32:33] op_sel_hi:[0,1,1] neg_lo:[0,0,1] neg_hi:[0,0,1]
	v_pk_mul_f32 v[32:33], v[148:149], v[130:131] op_sel_hi:[0,1]
	v_pk_fma_f32 v[42:43], v[92:93], v[40:41], v[32:33] op_sel_hi:[0,1,1] neg_lo:[0,0,1] neg_hi:[0,0,1]
	v_pk_mul_f32 v[32:33], v[148:149], v[124:125] op_sel_hi:[0,1]
	v_pk_fma_f32 v[34:35], v[92:93], v[46:47], v[32:33] op_sel_hi:[0,1,1] neg_lo:[0,0,1] neg_hi:[0,0,1]
	v_pk_mul_f32 v[32:33], v[148:149], v[110:111] op_sel_hi:[0,1]
	v_pk_fma_f32 v[40:41], v[92:93], v[44:45], v[32:33] op_sel_hi:[0,1,1] neg_lo:[0,0,1] neg_hi:[0,0,1]
	v_pk_mul_f32 v[32:33], v[148:149], v[104:105] op_sel_hi:[0,1]
	v_pk_fma_f32 v[32:33], v[92:93], v[18:19], v[32:33] op_sel_hi:[0,1,1] neg_lo:[0,0,1] neg_hi:[0,0,1]
	v_pk_mul_f32 v[18:19], v[148:149], v[102:103] op_sel_hi:[0,1]
	v_pk_fma_f32 v[36:37], v[92:93], v[16:17], v[18:19] op_sel_hi:[0,1,1] neg_lo:[0,0,1] neg_hi:[0,0,1]
	v_pk_mul_f32 v[16:17], v[148:149], v[100:101] op_sel_hi:[0,1]
	v_pk_fma_f32 v[22:23], v[92:93], v[22:23], v[16:17] op_sel_hi:[0,1,1] neg_lo:[0,0,1] neg_hi:[0,0,1]
	v_pk_mul_f32 v[16:17], v[148:149], v[98:99] op_sel_hi:[0,1]
	v_pk_mul_f32 v[116:117], v[148:149], v[116:117] op_sel_hi:[0,1]
; DI float bflo(unsigned u) { return __uint_as_float(u << 16); }
; DI float bfhi(unsigned u) { return __uint_as_float(u & 0xffff0000u); }
; DI float shx(float v, int m, int lane) { return __int_as_float(__builtin_amdgcn_ds_bpermute((lane ^ m) << 2, __float_as_int(v))); }
; __global__ void __launch_bounds__(512) mega(Params P) {
;     ...
;                         float ss = 0.f;
; #pragma unroll
;                         for (int d0 = 0; d0 < 4; ++d0)
; #pragma unroll
;                             for (int r = 0; r < 16; ++r) { const float v = o[d0][r] * linv - lam * xch[(d0 * 16 + r) * 256 + wid * 64 + l2]; o[d0][r] = v; ss += v * v; }
;                         ss += shx(ss, 32, l2);
;                         const float rn = rsqrtf(ss * (1.0f / 128.0f) + EPS) * (1.0f - lambda_init);
;                         const int token = q02 + (l2 & 31); const float* sw = P.diff_subnorm + l * 128;
; #pragma unroll
;                         for (int d0 = 0; d0 < 4; ++d0) {
; #pragma unroll
;                             for (int g = 0; g < 4; ++g) {
;                                 const int dv = 32 * d0 + 8 * g + 4 * hi2, col = 1536 + h2 * 128 + dv;
;                                 const u32x2 gv = *(const u32x2*)(proj + (size_t)token * LDP + C_SILU + col);
;                                 const f32x4 w = *(const f32x4*)(sw + dv);
;                                 u32x2 ov;
;                                 ov.x = cvt_pk(o[d0][4 * g + 0] * rn * w.x * bflo(gv.x), o[d0][4 * g + 1] * rn * w.y * bfhi(gv.x));
;                                 ov.y = cvt_pk(o[d0][4 * g + 2] * rn * w.z * bflo(gv.y), o[d0][4 * g + 3] * rn * w.w * bfhi(gv.y));
;                                 *(u32x2*)(Yb + (size_t)token * DM + col) = ov;
	v_pk_mul_f32 v[134:135], v[148:149], v[134:135] op_sel_hi:[0,1]
	v_pk_mul_f32 v[156:157], v[112:113], v[112:113]
	v_pk_fma_f32 v[20:21], v[92:93], v[20:21], v[16:17] op_sel_hi:[0,1,1] neg_lo:[0,0,1] neg_hi:[0,0,1]
	v_pk_mul_f32 v[16:17], v[148:149], v[96:97] op_sel_hi:[0,1]
	v_pk_mul_f32 v[18:19], v[148:149], v[94:95] op_sel_hi:[0,1]
	v_pk_fma_f32 v[28:29], v[92:93], v[28:29], v[116:117] op_sel_hi:[0,1,1] neg_lo:[0,0,1] neg_hi:[0,0,1]
	v_pk_fma_f32 v[30:31], v[92:93], v[30:31], v[134:135] op_sel_hi:[0,1,1] neg_lo:[0,0,1] neg_hi:[0,0,1]
	v_pk_mul_f32 v[154:155], v[106:107], v[106:107]
	v_pk_fma_f32 v[16:17], v[92:93], v[26:27], v[16:17] op_sel_hi:[0,1,1] neg_lo:[0,0,1] neg_hi:[0,0,1]
	v_pk_fma_f32 v[18:19], v[92:93], v[24:25], v[18:19] op_sel_hi:[0,1,1] neg_lo:[0,0,1] neg_hi:[0,0,1]
	v_add_f32_e32 v92, v156, v157
	v_add_f32_e32 v92, v92, v154
	v_pk_mul_f32 v[164:165], v[132:133], v[132:133]
	v_add_f32_e32 v92, v92, v155
	v_add_f32_e32 v92, v92, v164
	v_pk_mul_f32 v[162:163], v[114:115], v[114:115]
	v_add_f32_e32 v92, v92, v165
	v_add_f32_e32 v92, v92, v162
	v_pk_mul_f32 v[172:173], v[122:123], v[122:123]
	v_add_f32_e32 v92, v92, v163
	v_add_f32_e32 v92, v92, v172
	v_pk_mul_f32 v[170:171], v[108:109], v[108:109]
	v_add_f32_e32 v92, v92, v173
	v_add_f32_e32 v92, v92, v170
	v_pk_mul_f32 v[174:175], v[76:77], v[76:77]
	v_add_f32_e32 v92, v92, v171
	v_add_f32_e32 v92, v92, v174
	v_pk_mul_f32 v[78:79], v[72:73], v[72:73]
	v_add_f32_e32 v92, v92, v175
	v_add_f32_e32 v78, v92, v78
	v_pk_mul_f32 v[166:167], v[74:75], v[74:75]
	v_add_f32_e32 v78, v78, v79
	v_add_f32_e32 v78, v78, v166
	v_pk_mul_f32 v[168:169], v[68:69], v[68:69]
	v_add_f32_e32 v78, v78, v167
	v_add_f32_e32 v78, v78, v168
	v_pk_mul_f32 v[158:159], v[70:71], v[70:71]
	v_add_f32_e32 v78, v78, v169
	v_add_f32_e32 v78, v78, v158
	v_pk_mul_f32 v[160:161], v[64:65], v[64:65]
	v_add_f32_e32 v78, v78, v159
	v_add_f32_e32 v78, v78, v160
	v_pk_mul_f32 v[150:151], v[66:67], v[66:67]
	v_add_f32_e32 v78, v78, v161
	v_add_f32_e32 v78, v78, v150
	v_pk_mul_f32 v[152:153], v[58:59], v[58:59]
	v_add_f32_e32 v78, v78, v151
	v_add_f32_e32 v78, v78, v152
	v_pk_mul_f32 v[144:145], v[60:61], v[60:61]
	v_add_f32_e32 v78, v78, v153
	v_add_f32_e32 v78, v78, v144
	v_pk_mul_f32 v[62:63], v[54:55], v[54:55]
	v_add_f32_e32 v78, v78, v145
	v_add_f32_e32 v62, v78, v62
	v_pk_mul_f32 v[140:141], v[56:57], v[56:57]
	v_add_f32_e32 v62, v62, v63
	v_add_f32_e32 v62, v62, v140
	v_pk_mul_f32 v[142:143], v[50:51], v[50:51]
	v_add_f32_e32 v62, v62, v141
	v_add_f32_e32 v62, v62, v142
	v_pk_mul_f32 v[120:121], v[52:53], v[52:53]
	v_add_f32_e32 v62, v62, v143
	v_add_f32_e32 v62, v62, v120
	v_pk_mul_f32 v[126:127], v[48:49], v[48:49]
	v_add_f32_e32 v62, v62, v121
	v_add_f32_e32 v62, v62, v126
	v_pk_mul_f32 v[130:131], v[42:43], v[42:43]
	v_add_f32_e32 v62, v62, v127
	v_add_f32_e32 v62, v62, v130
	v_pk_mul_f32 v[138:139], v[38:39], v[38:39]
	v_add_f32_e32 v62, v62, v131
	v_add_f32_e32 v62, v62, v138
	v_pk_mul_f32 v[44:45], v[40:41], v[40:41]
	v_add_f32_e32 v62, v62, v139
	v_add_f32_e32 v44, v62, v44
	v_pk_mul_f32 v[46:47], v[34:35], v[34:35]
	v_add_f32_e32 v44, v44, v45
	v_add_f32_e32 v44, v44, v46
	v_pk_mul_f32 v[102:103], v[36:37], v[36:37]
	v_add_f32_e32 v44, v44, v47
	v_add_f32_e32 v44, v44, v102
	v_pk_mul_f32 v[104:105], v[32:33], v[32:33]
	v_add_f32_e32 v44, v44, v103
	v_add_f32_e32 v44, v44, v104
	v_pk_mul_f32 v[98:99], v[20:21], v[20:21]
	v_add_f32_e32 v44, v44, v105
	v_add_f32_e32 v44, v44, v98
	v_pk_mul_f32 v[100:101], v[22:23], v[22:23]
	v_add_f32_e32 v44, v44, v99
	v_add_f32_e32 v44, v44, v100
	v_pk_mul_f32 v[24:25], v[18:19], v[18:19]
	v_add_f32_e32 v44, v44, v101
	v_add_f32_e32 v24, v44, v24
	v_pk_mul_f32 v[26:27], v[16:17], v[16:17]
	v_add_f32_e32 v24, v24, v25
	v_add_f32_e32 v24, v24, v26
	v_pk_mul_f32 v[136:137], v[28:29], v[28:29]
	v_add_f32_e32 v24, v24, v27
	v_add_f32_e32 v24, v24, v136
	v_pk_mul_f32 v[134:135], v[30:31], v[30:31]
	v_add_f32_e32 v24, v24, v137
	v_add_f32_e32 v24, v24, v134
	v_add_f32_e32 v44, v24, v135
	ds_bpermute_b32 v45, v93, v44
	v_lshl_add_u64 v[24:25], s[48:49], 0, v[84:85]
	v_lshl_add_u64 v[26:27], v[24:25], 1, v[90:91]
	v_add_u32_e32 v62, 8, v84
	s_waitcnt vmcnt(16)
	v_lshlrev_b32_e32 v116, 16, v118
	s_waitcnt lgkmcnt(0)
	v_add_f32_e32 v24, v44, v45
	v_fmamk_f32 v24, v24, 0x3c000000, v218
	v_mul_f32_e32 v25, 0x4b800000, v24
	v_cmp_gt_f32_e32 vcc, s33, v24
	v_and_b32_e32 v117, 0xffff0000, v118
	v_lshlrev_b32_e32 v118, 16, v119
	v_cndmask_b32_e32 v24, v24, v25, vcc
	v_rsq_f32_e32 v44, v24
	v_add_u32_e32 v24, s50, v62
	v_ashrrev_i32_e32 v25, 31, v24
	v_lshl_add_u64 v[78:79], v[24:25], 1, v[86:87]
	v_mul_f32_e32 v24, 0x45800000, v44
	v_cndmask_b32_e32 v24, v44, v24, vcc
	v_sub_f32_e32 v25, 1.0, v183
	v_mul_f32_e32 v24, v25, v24
	v_pk_mul_f32 v[44:45], v[24:25], v[112:113] op_sel_hi:[0,1]
	v_pk_mul_f32 v[46:47], v[24:25], v[106:107] op_sel_hi:[0,1]
	v_and_b32_e32 v119, 0xffff0000, v119
	s_waitcnt vmcnt(0)
; DI float bflo(unsigned u) { return __uint_as_float(u << 16); }
; DI float bfhi(unsigned u) { return __uint_as_float(u & 0xffff0000u); }
; __global__ void __launch_bounds__(512) mega(Params P) {
;     ...
;                         const int token = q02 + (l2 & 31); const float* sw = P.diff_subnorm + l * 128;
; #pragma unroll
;                         for (int d0 = 0; d0 < 4; ++d0) {
; #pragma unroll
;                             for (int g = 0; g < 4; ++g) {
;                                 const int dv = 32 * d0 + 8 * g + 4 * hi2, col = 1536 + h2 * 128 + dv;
;                                 const u32x2 gv = *(const u32x2*)(proj + (size_t)token * LDP + C_SILU + col);
;                                 const f32x4 w = *(const f32x4*)(sw + dv);
;                                 u32x2 ov;
;                                 ov.x = cvt_pk(o[d0][4 * g + 0] * rn * w.x * bflo(gv.x), o[d0][4 * g + 1] * rn * w.y * bfhi(gv.x));
;                                 ov.y = cvt_pk(o[d0][4 * g + 2] * rn * w.z * bflo(gv.y), o[d0][4 * g + 3] * rn * w.w * bfhi(gv.y));
;                                 *(u32x2*)(Yb + (size_t)token * DM + col) = ov;
;                             }
;                             asm volatile("" ::: "memory");
;                         }
	v_pk_mul_f32 v[44:45], v[80:81], v[44:45]
	v_pk_mul_f32 v[46:47], v[82:83], v[46:47]
	v_pk_mul_f32 v[44:45], v[44:45], v[116:117]
	v_pk_mul_f32 v[46:47], v[46:47], v[118:119]
	v_cvt_pk_bf16_f32 v44, v44, v45
	v_cvt_pk_bf16_f32 v45, v46, v47
	global_store_dwordx2 v[26:27], v[44:45], off offset:3072
	global_load_dwordx4 v[44:47], v[88:89], off offset:32
	global_load_dwordx4 v[134:137], v[88:89], off offset:64
	global_load_dwordx4 v[138:141], v[88:89], off offset:96
	global_load_dwordx4 v[142:145], v[88:89], off offset:128
	global_load_dwordx4 v[146:149], v[88:89], off offset:160
	global_load_dwordx4 v[150:153], v[88:89], off offset:192
	global_load_dwordx4 v[154:157], v[88:89], off offset:224
	global_load_dwordx4 v[158:161], v[88:89], off offset:256
	global_load_dwordx4 v[162:165], v[88:89], off offset:288
	global_load_dwordx4 v[166:169], v[88:89], off offset:320
	global_load_dwordx4 v[170:173], v[88:89], off offset:352
	global_load_dwordx4 v[174:177], v[88:89], off offset:384
	global_load_dwordx4 v[94:97], v[88:89], off offset:416
	global_load_dwordx4 v[98:101], v[88:89], off offset:448
	global_load_dwordx4 v[102:105], v[88:89], off offset:480
	s_nop 0
	v_mov_b64_e32 v[26:27], v[222:223]
	v_pk_mul_f32 v[82:83], v[24:25], v[132:133] op_sel_hi:[0,1]
	v_ashrrev_i32_e32 v63, 31, v62
	v_lshl_add_u64 v[62:63], s[48:49], 0, v[62:63]
	v_add_u32_e32 v78, 16, v84
	v_lshl_add_u64 v[62:63], v[62:63], 1, v[90:91]
	v_add_u32_e32 v80, s50, v78
	v_ashrrev_i32_e32 v81, 31, v80
	v_lshl_add_u64 v[80:81], v[80:81], 1, v[86:87]
	v_pk_mul_f32 v[92:93], v[24:25], v[108:109] op_sel_hi:[0,1]
	v_ashrrev_i32_e32 v79, 31, v78
	v_lshl_add_u64 v[78:79], s[48:49], 0, v[78:79]
	v_lshl_add_u64 v[78:79], v[78:79], 1, v[90:91]
	v_pk_mul_f32 v[76:77], v[24:25], v[76:77] op_sel_hi:[0,1]
	v_pk_mul_f32 v[72:73], v[24:25], v[72:73] op_sel_hi:[0,1]
	v_pk_mul_f32 v[74:75], v[24:25], v[74:75] op_sel_hi:[0,1]
	v_pk_mul_f32 v[68:69], v[24:25], v[68:69] op_sel_hi:[0,1]
	v_pk_mul_f32 v[70:71], v[24:25], v[70:71] op_sel_hi:[0,1]
	v_pk_mul_f32 v[64:65], v[24:25], v[64:65] op_sel_hi:[0,1]
	v_pk_mul_f32 v[66:67], v[24:25], v[66:67] op_sel_hi:[0,1]
	v_pk_mul_f32 v[58:59], v[24:25], v[58:59] op_sel_hi:[0,1]
	v_pk_mul_f32 v[60:61], v[24:25], v[60:61] op_sel_hi:[0,1]
	v_pk_mul_f32 v[54:55], v[24:25], v[54:55] op_sel_hi:[0,1]
	v_pk_mul_f32 v[56:57], v[24:25], v[56:57] op_sel_hi:[0,1]
	v_pk_mul_f32 v[50:51], v[24:25], v[50:51] op_sel_hi:[0,1]
	v_pk_mul_f32 v[52:53], v[24:25], v[52:53] op_sel_hi:[0,1]
	v_pk_mul_f32 v[48:49], v[24:25], v[48:49] op_sel_hi:[0,1]
	v_pk_mul_f32 v[42:43], v[24:25], v[42:43] op_sel_hi:[0,1]
	v_pk_mul_f32 v[38:39], v[24:25], v[38:39] op_sel_hi:[0,1]
	v_pk_mul_f32 v[34:35], v[24:25], v[34:35] op_sel_hi:[0,1]
	v_pk_mul_f32 v[32:33], v[24:25], v[32:33] op_sel_hi:[0,1]
	v_pk_mul_f32 v[20:21], v[24:25], v[20:21] op_sel_hi:[0,1]
	v_pk_mul_f32 v[22:23], v[24:25], v[22:23] op_sel_hi:[0,1]
	v_pk_mul_f32 v[18:19], v[24:25], v[18:19] op_sel_hi:[0,1]
	v_pk_mul_f32 v[16:17], v[24:25], v[16:17] op_sel_hi:[0,1]
	s_waitcnt vmcnt(14)
	v_pk_mul_f32 v[44:45], v[44:45], v[82:83]
	s_waitcnt vmcnt(14)
	v_lshlrev_b32_e32 v82, 16, v26
	v_and_b32_e32 v83, 0xffff0000, v26
	v_pk_mul_f32 v[44:45], v[44:45], v[82:83]
	v_pk_mul_f32 v[82:83], v[24:25], v[122:123] op_sel_hi:[0,1]
	v_cvt_pk_bf16_f32 v26, v44, v45
	v_pk_mul_f32 v[44:45], v[24:25], v[114:115] op_sel_hi:[0,1]
	v_pk_mul_f32 v[44:45], v[46:47], v[44:45]
	v_lshlrev_b32_e32 v46, 16, v27
	v_and_b32_e32 v47, 0xffff0000, v27
	v_pk_mul_f32 v[44:45], v[44:45], v[46:47]
	s_nop 0
	v_cvt_pk_bf16_f32 v27, v44, v45
	global_store_dwordx2 v[62:63], v[26:27], off offset:3072
	s_waitcnt vmcnt(14)
	v_mov_b64_e32 v[44:45], v[134:135]
	v_mov_b64_e32 v[46:47], v[136:137]
	s_nop 0
	v_mov_b64_e32 v[26:27], v[224:225]
	v_add_u32_e32 v62, 24, v84
	v_add_u32_e32 v80, s50, v62
	v_ashrrev_i32_e32 v81, 31, v80
	v_lshl_add_u64 v[80:81], v[80:81], 1, v[86:87]
	v_ashrrev_i32_e32 v63, 31, v62
	v_lshl_add_u64 v[62:63], s[48:49], 0, v[62:63]
	v_lshl_add_u64 v[62:63], v[62:63], 1, v[90:91]
	s_waitcnt vmcnt(14)
	v_pk_mul_f32 v[44:45], v[44:45], v[82:83]
	s_waitcnt vmcnt(14)
	v_lshlrev_b32_e32 v82, 16, v26
	v_and_b32_e32 v83, 0xffff0000, v26
	v_pk_mul_f32 v[46:47], v[46:47], v[92:93]
	v_lshlrev_b32_e32 v26, 16, v27
	v_and_b32_e32 v27, 0xffff0000, v27
	v_pk_mul_f32 v[44:45], v[44:45], v[82:83]
	v_pk_mul_f32 v[26:27], v[46:47], v[26:27]
	v_cvt_pk_bf16_f32 v44, v44, v45
	v_cvt_pk_bf16_f32 v45, v26, v27
	global_store_dwordx2 v[78:79], v[44:45], off offset:3072
	s_waitcnt vmcnt(14)
	v_mov_b64_e32 v[44:45], v[138:139]
	v_mov_b64_e32 v[46:47], v[140:141]
	s_nop 0
	v_mov_b64_e32 v[26:27], v[226:227]
	v_add_u32_e32 v78, 32, v84
	v_add_u32_e32 v80, s50, v78
	v_ashrrev_i32_e32 v81, 31, v80
	v_lshl_add_u64 v[80:81], v[80:81], 1, v[86:87]
	v_ashrrev_i32_e32 v79, 31, v78
	s_waitcnt vmcnt(14)
	v_pk_mul_f32 v[44:45], v[44:45], v[76:77]
	s_waitcnt vmcnt(14)
	v_lshlrev_b32_e32 v76, 16, v26
	v_and_b32_e32 v77, 0xffff0000, v26
	v_pk_mul_f32 v[46:47], v[46:47], v[72:73]
	v_lshlrev_b32_e32 v26, 16, v27
	v_and_b32_e32 v27, 0xffff0000, v27
	v_pk_mul_f32 v[44:45], v[44:45], v[76:77]
	v_pk_mul_f32 v[26:27], v[46:47], v[26:27]
	v_cvt_pk_bf16_f32 v44, v44, v45
	v_cvt_pk_bf16_f32 v45, v26, v27
	global_store_dwordx2 v[62:63], v[44:45], off offset:3072
	s_waitcnt vmcnt(14)
	v_mov_b64_e32 v[44:45], v[142:143]
	v_mov_b64_e32 v[46:47], v[144:145]
	v_mov_b64_e32 v[26:27], v[228:229]
	v_add_u32_e32 v62, 40, v84
	v_lshl_add_u64 v[76:77], s[48:49], 0, v[78:79]
	v_add_u32_e32 v72, s50, v62
	v_lshl_add_u64 v[76:77], v[76:77], 1, v[90:91]
	v_ashrrev_i32_e32 v73, 31, v72
	v_lshl_add_u64 v[72:73], v[72:73], 1, v[86:87]
	v_ashrrev_i32_e32 v63, 31, v62
	v_lshl_add_u64 v[62:63], s[48:49], 0, v[62:63]
	v_lshl_add_u64 v[62:63], v[62:63], 1, v[90:91]
	s_waitcnt vmcnt(14)
; DI float bflo(unsigned u) { return __uint_as_float(u << 16); }
; DI float bfhi(unsigned u) { return __uint_as_float(u & 0xffff0000u); }
; __global__ void __launch_bounds__(512) mega(Params P) {
;     ...
;                         const int token = q02 + (l2 & 31); const float* sw = P.diff_subnorm + l * 128;
; #pragma unroll
;                         for (int d0 = 0; d0 < 4; ++d0) {
; #pragma unroll
;                             for (int g = 0; g < 4; ++g) {
;                                 const int dv = 32 * d0 + 8 * g + 4 * hi2, col = 1536 + h2 * 128 + dv;
;                                 const u32x2 gv = *(const u32x2*)(proj + (size_t)token * LDP + C_SILU + col);
;                                 const f32x4 w = *(const f32x4*)(sw + dv);
;                                 u32x2 ov;
;                                 ov.x = cvt_pk(o[d0][4 * g + 0] * rn * w.x * bflo(gv.x), o[d0][4 * g + 1] * rn * w.y * bfhi(gv.x));
;                                 ov.y = cvt_pk(o[d0][4 * g + 2] * rn * w.z * bflo(gv.y), o[d0][4 * g + 3] * rn * w.w * bfhi(gv.y));
;                                 *(u32x2*)(Yb + (size_t)token * DM + col) = ov;
;                             }
;                             asm volatile("" ::: "memory");
;                         }
	v_pk_mul_f32 v[44:45], v[44:45], v[74:75]
	s_waitcnt vmcnt(14)
	v_lshlrev_b32_e32 v74, 16, v26
	v_and_b32_e32 v75, 0xffff0000, v26
	v_pk_mul_f32 v[46:47], v[46:47], v[68:69]
	v_lshlrev_b32_e32 v26, 16, v27
	v_and_b32_e32 v27, 0xffff0000, v27
	v_pk_mul_f32 v[44:45], v[44:45], v[74:75]
	v_pk_mul_f32 v[26:27], v[46:47], v[26:27]
	v_cvt_pk_bf16_f32 v44, v44, v45
	v_cvt_pk_bf16_f32 v45, v26, v27
	global_store_dwordx2 v[76:77], v[44:45], off offset:3072
	s_waitcnt vmcnt(14)
	v_mov_b64_e32 v[44:45], v[146:147]
	v_mov_b64_e32 v[46:47], v[148:149]
	s_nop 0
	v_mov_b64_e32 v[26:27], v[230:231]
	v_add_u32_e32 v68, 48, v84
	v_add_u32_e32 v72, s50, v68
	v_ashrrev_i32_e32 v73, 31, v72
	v_lshl_add_u64 v[72:73], v[72:73], 1, v[86:87]
	v_ashrrev_i32_e32 v69, 31, v68
	v_lshl_add_u64 v[68:69], s[48:49], 0, v[68:69]
	v_lshl_add_u64 v[68:69], v[68:69], 1, v[90:91]
	s_waitcnt vmcnt(14)
	v_pk_mul_f32 v[44:45], v[44:45], v[70:71]
	s_waitcnt vmcnt(14)
	v_lshlrev_b32_e32 v70, 16, v26
	v_and_b32_e32 v71, 0xffff0000, v26
	v_pk_mul_f32 v[46:47], v[46:47], v[64:65]
	v_lshlrev_b32_e32 v26, 16, v27
	v_and_b32_e32 v27, 0xffff0000, v27
	v_pk_mul_f32 v[44:45], v[44:45], v[70:71]
	v_pk_mul_f32 v[26:27], v[46:47], v[26:27]
	v_cvt_pk_bf16_f32 v44, v44, v45
	v_cvt_pk_bf16_f32 v45, v26, v27
	global_store_dwordx2 v[62:63], v[44:45], off offset:3072
	s_waitcnt vmcnt(14)
	v_mov_b64_e32 v[44:45], v[150:151]
	v_mov_b64_e32 v[46:47], v[152:153]
	s_nop 0
	v_mov_b64_e32 v[26:27], v[232:233]
	v_add_u32_e32 v62, 56, v84
	v_add_u32_e32 v64, s50, v62
	v_ashrrev_i32_e32 v65, 31, v64
	v_lshl_add_u64 v[64:65], v[64:65], 1, v[86:87]
	v_ashrrev_i32_e32 v63, 31, v62
	v_lshl_add_u64 v[62:63], s[48:49], 0, v[62:63]
	v_lshl_add_u64 v[62:63], v[62:63], 1, v[90:91]
	s_waitcnt vmcnt(14)
	v_pk_mul_f32 v[44:45], v[44:45], v[66:67]
	s_waitcnt vmcnt(14)
	v_lshlrev_b32_e32 v66, 16, v26
	v_and_b32_e32 v67, 0xffff0000, v26
	v_pk_mul_f32 v[46:47], v[46:47], v[58:59]
	v_lshlrev_b32_e32 v26, 16, v27
	v_and_b32_e32 v27, 0xffff0000, v27
	v_pk_mul_f32 v[44:45], v[44:45], v[66:67]
	v_pk_mul_f32 v[26:27], v[46:47], v[26:27]
	v_cvt_pk_bf16_f32 v44, v44, v45
	v_cvt_pk_bf16_f32 v45, v26, v27
	global_store_dwordx2 v[68:69], v[44:45], off offset:3072
	s_waitcnt vmcnt(14)
	v_mov_b64_e32 v[44:45], v[154:155]
	v_mov_b64_e32 v[46:47], v[156:157]
	s_nop 0
	v_mov_b64_e32 v[26:27], v[234:235]
	v_add_u32_e32 v58, 64, v84
	v_add_u32_e32 v64, s50, v58
	v_ashrrev_i32_e32 v65, 31, v64
	v_lshl_add_u64 v[64:65], v[64:65], 1, v[86:87]
	v_ashrrev_i32_e32 v59, 31, v58
	v_lshl_add_u64 v[58:59], s[48:49], 0, v[58:59]
	v_lshl_add_u64 v[58:59], v[58:59], 1, v[90:91]
	s_waitcnt vmcnt(14)
	v_pk_mul_f32 v[44:45], v[44:45], v[60:61]
	s_waitcnt vmcnt(14)
	v_lshlrev_b32_e32 v60, 16, v26
	v_and_b32_e32 v61, 0xffff0000, v26
	v_pk_mul_f32 v[46:47], v[46:47], v[54:55]
	v_lshlrev_b32_e32 v26, 16, v27
	v_and_b32_e32 v27, 0xffff0000, v27
	v_pk_mul_f32 v[44:45], v[44:45], v[60:61]
	v_pk_mul_f32 v[26:27], v[46:47], v[26:27]
	v_cvt_pk_bf16_f32 v44, v44, v45
	v_cvt_pk_bf16_f32 v45, v26, v27
	global_store_dwordx2 v[62:63], v[44:45], off offset:3072
	s_waitcnt vmcnt(14)
	v_mov_b64_e32 v[44:45], v[158:159]
	v_mov_b64_e32 v[46:47], v[160:161]
	v_mov_b64_e32 v[26:27], v[236:237]
	v_add_u32_e32 v54, 0x48, v84
	v_add_u32_e32 v60, s50, v54
	v_ashrrev_i32_e32 v61, 31, v60
	v_lshl_add_u64 v[60:61], v[60:61], 1, v[86:87]
	v_ashrrev_i32_e32 v55, 31, v54
	v_lshl_add_u64 v[54:55], s[48:49], 0, v[54:55]
	v_lshl_add_u64 v[54:55], v[54:55], 1, v[90:91]
	s_waitcnt vmcnt(14)
	v_pk_mul_f32 v[44:45], v[44:45], v[56:57]
	s_waitcnt vmcnt(14)
	v_lshlrev_b32_e32 v56, 16, v26
	v_and_b32_e32 v57, 0xffff0000, v26
	v_pk_mul_f32 v[46:47], v[46:47], v[50:51]
	v_lshlrev_b32_e32 v26, 16, v27
	v_and_b32_e32 v27, 0xffff0000, v27
	v_pk_mul_f32 v[44:45], v[44:45], v[56:57]
	v_pk_mul_f32 v[26:27], v[46:47], v[26:27]
	v_cvt_pk_bf16_f32 v44, v44, v45
	v_cvt_pk_bf16_f32 v45, v26, v27
	global_store_dwordx2 v[58:59], v[44:45], off offset:3072
	s_waitcnt vmcnt(14)
	v_mov_b64_e32 v[44:45], v[162:163]
	v_mov_b64_e32 v[46:47], v[164:165]
	s_nop 0
	v_mov_b64_e32 v[26:27], v[238:239]
	v_add_u32_e32 v50, 0x50, v84
	v_add_u32_e32 v56, s50, v50
	v_ashrrev_i32_e32 v57, 31, v56
	v_lshl_add_u64 v[56:57], v[56:57], 1, v[86:87]
	v_ashrrev_i32_e32 v51, 31, v50
	v_lshl_add_u64 v[50:51], s[48:49], 0, v[50:51]
	v_lshl_add_u64 v[50:51], v[50:51], 1, v[90:91]
	s_waitcnt vmcnt(14)
	v_pk_mul_f32 v[44:45], v[44:45], v[52:53]
	s_waitcnt vmcnt(14)
	v_lshlrev_b32_e32 v52, 16, v26
	v_and_b32_e32 v53, 0xffff0000, v26
	v_pk_mul_f32 v[46:47], v[46:47], v[48:49]
	v_lshlrev_b32_e32 v26, 16, v27
	v_and_b32_e32 v27, 0xffff0000, v27
	v_pk_mul_f32 v[44:45], v[44:45], v[52:53]
	v_pk_mul_f32 v[26:27], v[46:47], v[26:27]
	v_cvt_pk_bf16_f32 v44, v44, v45
	v_cvt_pk_bf16_f32 v45, v26, v27
	global_store_dwordx2 v[54:55], v[44:45], off offset:3072
	s_waitcnt vmcnt(14)
; DI float bflo(unsigned u) { return __uint_as_float(u << 16); }
; DI float bfhi(unsigned u) { return __uint_as_float(u & 0xffff0000u); }
; __global__ void __launch_bounds__(512) mega(Params P) {
;     ...
;                         const int token = q02 + (l2 & 31); const float* sw = P.diff_subnorm + l * 128;
; #pragma unroll
;                         for (int d0 = 0; d0 < 4; ++d0) {
; #pragma unroll
;                             for (int g = 0; g < 4; ++g) {
;                                 const int dv = 32 * d0 + 8 * g + 4 * hi2, col = 1536 + h2 * 128 + dv;
;                                 const u32x2 gv = *(const u32x2*)(proj + (size_t)token * LDP + C_SILU + col);
;                                 const f32x4 w = *(const f32x4*)(sw + dv);
;                                 u32x2 ov;
;                                 ov.x = cvt_pk(o[d0][4 * g + 0] * rn * w.x * bflo(gv.x), o[d0][4 * g + 1] * rn * w.y * bfhi(gv.x));
;                                 ov.y = cvt_pk(o[d0][4 * g + 2] * rn * w.z * bflo(gv.y), o[d0][4 * g + 3] * rn * w.w * bfhi(gv.y));
;                                 *(u32x2*)(Yb + (size_t)token * DM + col) = ov;
;                             }
;                             asm volatile("" ::: "memory");
;                         }
	v_mov_b64_e32 v[44:45], v[166:167]
	v_mov_b64_e32 v[46:47], v[168:169]
	s_nop 0
	v_mov_b64_e32 v[26:27], v[240:241]
	v_add_u32_e32 v48, 0x58, v84
	v_add_u32_e32 v52, s50, v48
	v_ashrrev_i32_e32 v53, 31, v52
	v_lshl_add_u64 v[52:53], v[52:53], 1, v[86:87]
	v_ashrrev_i32_e32 v49, 31, v48
	v_lshl_add_u64 v[48:49], s[48:49], 0, v[48:49]
	v_lshl_add_u64 v[48:49], v[48:49], 1, v[90:91]
	s_waitcnt vmcnt(14)
	v_pk_mul_f32 v[42:43], v[44:45], v[42:43]
	s_waitcnt vmcnt(14)
	v_lshlrev_b32_e32 v44, 16, v26
	v_and_b32_e32 v45, 0xffff0000, v26
	v_pk_mul_f32 v[38:39], v[46:47], v[38:39]
	v_lshlrev_b32_e32 v26, 16, v27
	v_and_b32_e32 v27, 0xffff0000, v27
	v_pk_mul_f32 v[42:43], v[42:43], v[44:45]
	v_pk_mul_f32 v[26:27], v[38:39], v[26:27]
	v_cvt_pk_bf16_f32 v38, v42, v43
	v_cvt_pk_bf16_f32 v39, v26, v27
	global_store_dwordx2 v[50:51], v[38:39], off offset:3072
	s_waitcnt vmcnt(14)
	v_mov_b64_e32 v[42:43], v[170:171]
	v_mov_b64_e32 v[44:45], v[172:173]
	v_mov_b64_e32 v[26:27], v[242:243]
	v_add_u32_e32 v46, 0x60, v84
	v_add_u32_e32 v38, s50, v46
	v_ashrrev_i32_e32 v39, 31, v38
	v_lshl_add_u64 v[50:51], v[38:39], 1, v[86:87]
	v_pk_mul_f32 v[38:39], v[24:25], v[40:41] op_sel_hi:[0,1]
	v_ashrrev_i32_e32 v47, 31, v46
	s_waitcnt vmcnt(14)
	v_pk_mul_f32 v[38:39], v[42:43], v[38:39]
	s_waitcnt vmcnt(14)
	v_lshlrev_b32_e32 v40, 16, v26
	v_and_b32_e32 v41, 0xffff0000, v26
	v_pk_mul_f32 v[34:35], v[44:45], v[34:35]
	v_lshlrev_b32_e32 v26, 16, v27
	v_and_b32_e32 v27, 0xffff0000, v27
	v_pk_mul_f32 v[38:39], v[38:39], v[40:41]
	v_pk_mul_f32 v[26:27], v[34:35], v[26:27]
	v_cvt_pk_bf16_f32 v34, v38, v39
	v_cvt_pk_bf16_f32 v35, v26, v27
	global_store_dwordx2 v[48:49], v[34:35], off offset:3072
	s_waitcnt vmcnt(14)
	v_mov_b64_e32 v[38:39], v[174:175]
	v_mov_b64_e32 v[40:41], v[176:177]
	v_mov_b64_e32 v[26:27], v[244:245]
	v_add_u32_e32 v42, 0x68, v84
	v_add_u32_e32 v34, s50, v42
	v_ashrrev_i32_e32 v35, 31, v34
	v_lshl_add_u64 v[44:45], s[48:49], 0, v[46:47]
	v_lshl_add_u64 v[46:47], v[34:35], 1, v[86:87]
	v_pk_mul_f32 v[34:35], v[24:25], v[36:37] op_sel_hi:[0,1]
	v_lshl_add_u64 v[44:45], v[44:45], 1, v[90:91]
	v_ashrrev_i32_e32 v43, 31, v42
	s_waitcnt vmcnt(14)
	v_pk_mul_f32 v[34:35], v[38:39], v[34:35]
	s_waitcnt vmcnt(14)
	v_lshlrev_b32_e32 v36, 16, v26
	v_and_b32_e32 v37, 0xffff0000, v26
	v_pk_mul_f32 v[32:33], v[40:41], v[32:33]
	v_lshlrev_b32_e32 v26, 16, v27
	v_and_b32_e32 v27, 0xffff0000, v27
	v_pk_mul_f32 v[34:35], v[34:35], v[36:37]
	v_pk_mul_f32 v[26:27], v[32:33], v[26:27]
	v_cvt_pk_bf16_f32 v32, v34, v35
	v_cvt_pk_bf16_f32 v33, v26, v27
	global_store_dwordx2 v[44:45], v[32:33], off offset:3072
	s_waitcnt vmcnt(14)
	v_mov_b64_e32 v[32:33], v[94:95]
	v_mov_b64_e32 v[34:35], v[96:97]
	s_nop 0
	v_mov_b64_e32 v[26:27], v[246:247]
	v_add_u32_e32 v36, 0x70, v84
	v_lshl_add_u64 v[40:41], s[48:49], 0, v[42:43]
	v_add_u32_e32 v38, s50, v36
	v_lshl_add_u64 v[40:41], v[40:41], 1, v[90:91]
	v_ashrrev_i32_e32 v39, 31, v38
	v_lshl_add_u64 v[38:39], v[38:39], 1, v[86:87]
	v_ashrrev_i32_e32 v37, 31, v36
	v_lshl_add_u64 v[36:37], s[48:49], 0, v[36:37]
	v_lshl_add_u64 v[36:37], v[36:37], 1, v[90:91]
	s_waitcnt vmcnt(14)
	v_pk_mul_f32 v[20:21], v[32:33], v[20:21]
	s_waitcnt vmcnt(14)
	v_lshlrev_b32_e32 v32, 16, v26
	v_and_b32_e32 v33, 0xffff0000, v26
	v_pk_mul_f32 v[22:23], v[34:35], v[22:23]
	v_lshlrev_b32_e32 v26, 16, v27
	v_and_b32_e32 v27, 0xffff0000, v27
	v_pk_mul_f32 v[20:21], v[20:21], v[32:33]
	v_pk_mul_f32 v[22:23], v[22:23], v[26:27]
	v_cvt_pk_bf16_f32 v20, v20, v21
	v_cvt_pk_bf16_f32 v21, v22, v23
	global_store_dwordx2 v[40:41], v[20:21], off offset:3072
	s_waitcnt vmcnt(14)
	v_mov_b64_e32 v[20:21], v[98:99]
	v_mov_b64_e32 v[22:23], v[100:101]
	s_nop 0
	v_mov_b64_e32 v[26:27], v[248:249]
	v_add_u32_e32 v32, 0x78, v84
	v_add_u32_e32 v34, s50, v32
	v_ashrrev_i32_e32 v35, 31, v34
	v_lshl_add_u64 v[34:35], v[34:35], 1, v[86:87]
	v_ashrrev_i32_e32 v33, 31, v32
	s_waitcnt vmcnt(14)
	v_pk_mul_f32 v[18:19], v[20:21], v[18:19]
	s_waitcnt vmcnt(14)
	v_lshlrev_b32_e32 v20, 16, v26
	v_and_b32_e32 v21, 0xffff0000, v26
	v_pk_mul_f32 v[16:17], v[22:23], v[16:17]
	v_lshlrev_b32_e32 v22, 16, v27
	v_and_b32_e32 v23, 0xffff0000, v27
	v_pk_mul_f32 v[18:19], v[18:19], v[20:21]
	v_pk_mul_f32 v[16:17], v[16:17], v[22:23]
	v_cvt_pk_bf16_f32 v18, v18, v19
	v_cvt_pk_bf16_f32 v19, v16, v17
	global_store_dwordx2 v[36:37], v[18:19], off offset:3072
	s_waitcnt vmcnt(14)
	v_mov_b64_e32 v[16:17], v[102:103]
	v_mov_b64_e32 v[18:19], v[104:105]
	s_nop 0
	v_mov_b64_e32 v[20:21], v[250:251]
	v_pk_mul_f32 v[26:27], v[24:25], v[28:29] op_sel_hi:[0,1]
	v_pk_mul_f32 v[24:25], v[24:25], v[30:31] op_sel_hi:[0,1]
	v_lshl_add_u64 v[22:23], s[48:49], 0, v[32:33]
	s_waitcnt vmcnt(14)
	v_pk_mul_f32 v[16:17], v[16:17], v[26:27]
	s_waitcnt vmcnt(14)
	v_lshlrev_b32_e32 v26, 16, v20
	v_and_b32_e32 v27, 0xffff0000, v20
	v_pk_mul_f32 v[18:19], v[18:19], v[24:25]
	v_lshlrev_b32_e32 v20, 16, v21
	v_and_b32_e32 v21, 0xffff0000, v21
	v_pk_mul_f32 v[16:17], v[16:17], v[26:27]
	v_pk_mul_f32 v[18:19], v[18:19], v[20:21]
	v_cvt_pk_bf16_f32 v16, v16, v17
	v_cvt_pk_bf16_f32 v17, v18, v19
	v_lshl_add_u64 v[18:19], v[22:23], 1, v[90:91]
	global_store_dwordx2 v[18:19], v[16:17], off offset:3072
	s_branch .LBB0_450
